# defer second half of softmax-1 row-sum adds into the PV1 MFMA block (V frag regs renamed)
# speedup vs baseline: 1.0355x; 1.0044x over previous
; #define VWAIT(N, f) asm volatile("s_waitcnt lgkmcnt(" #N ")" : "+v"(f.l0), "+v"(f.h0), "+v"(f.l1), "+v"(f.h1) :: "memory")
; template <int H> __device__ __forceinline__ void pv_half(f32x16* o, int vb, bf16x8 paL, bf16x8 paH) {
;   VFrag fa = pv_rd<H, 0>(vb), fb = pv_rd<H, 1>(vb);
;   VWAIT(4, fa); pv_mma(o[0], fa, paL, paH);
;   fa = pv_rd<H, 2>(vb);
;   VWAIT(4, fb); pv_mma(o[1], fb, paL, paH);
;   fb = pv_rd<H, 3>(vb);
;   VWAIT(4, fa); pv_mma(o[2], fa, paL, paH);
;   VWAIT(0, fb); pv_mma(o[3], fb, paL, paH);
; }
.LBB0_517:
	s_or_b64 exec, exec, s[64:65]
	s_waitcnt lgkmcnt(0)
	v_add_u32_e32 v88, s80, v176
	ds_read_b128 v[204:207], v88 offset:224
	ds_read_b128 v[208:211], v88 offset:192
	ds_read_b128 v[84:87], v88 offset:160
	ds_read_b128 v[94:97], v88 offset:128
	s_waitcnt lgkmcnt(0)
	v_pk_mul_f32 v[62:63], v[62:63], v[204:205]
	v_pk_mul_f32 v[58:59], v[58:59], v[208:209]
	v_pk_mul_f32 v[54:55], v[54:55], v[84:85]
	v_pk_mul_f32 v[64:65], v[64:65], v[206:207]
	v_pk_mul_f32 v[60:61], v[60:61], v[210:211]
	v_pk_mul_f32 v[56:57], v[56:57], v[86:87]
	v_pk_mul_f32 v[52:53], v[52:53], v[96:97]
	v_pk_mul_f32 v[50:51], v[50:51], v[94:95]
	v_pk_mul_f32 v[46:47], v[46:47], v[204:205]
	v_pk_mul_f32 v[42:43], v[42:43], v[208:209]
	v_pk_mul_f32 v[38:39], v[38:39], v[84:85]
	v_pk_mul_f32 v[48:49], v[48:49], v[206:207]
	v_pk_mul_f32 v[44:45], v[44:45], v[210:211]
	v_pk_mul_f32 v[40:41], v[40:41], v[86:87]
	v_pk_mul_f32 v[36:37], v[36:37], v[96:97]
	v_pk_mul_f32 v[34:35], v[34:35], v[94:95]
	v_pk_mul_f32 v[30:31], v[30:31], v[204:205]
	v_pk_mul_f32 v[26:27], v[26:27], v[208:209]
	v_pk_mul_f32 v[22:23], v[22:23], v[84:85]
	v_pk_mul_f32 v[32:33], v[32:33], v[206:207]
	v_pk_mul_f32 v[28:29], v[28:29], v[210:211]
	v_pk_mul_f32 v[24:25], v[24:25], v[86:87]
	v_pk_mul_f32 v[20:21], v[20:21], v[96:97]
	v_pk_mul_f32 v[18:19], v[18:19], v[94:95]
	v_pk_mul_f32 v[14:15], v[14:15], v[204:205]
	v_pk_mul_f32 v[10:11], v[10:11], v[208:209]
	v_pk_mul_f32 v[6:7], v[6:7], v[84:85]
	v_pk_mul_f32 v[16:17], v[16:17], v[206:207]
	v_pk_mul_f32 v[12:13], v[12:13], v[210:211]
	v_pk_mul_f32 v[8:9], v[8:9], v[86:87]
	v_pk_mul_f32 v[4:5], v[4:5], v[96:97]
	v_pk_mul_f32 v[2:3], v[2:3], v[94:95]
.LBB0_518:
	v_fma_f32 v202, v197, v0, v198
	v_fma_f32 v0, v202, v200, v201
	v_fma_f32 v202, v0, v249, v91
	ds_read_b64_tr_b16 v[204:205], v181 offset:0x2000
	ds_read_b64_tr_b16 v[206:207], v181 offset:0x2800
	ds_read_b64_tr_b16 v[208:209], v181 offset:0x3000
	ds_read_b64_tr_b16 v[210:211], v181 offset:0x3800
	ds_read_b64_tr_b16 v[82:83], v181 offset:0x2200
	ds_read_b64_tr_b16 v[84:85], v181 offset:0x2a00
	ds_read_b64_tr_b16 v[86:87], v181 offset:0x3200
	ds_read_b64_tr_b16 v[88:89], v181 offset:0x3a00
	s_waitcnt lgkmcnt(4)
	v_mfma_f32_32x32x16_bf16 v[50:65], v[66:69], v[204:207], v[50:65]
	v_add_f32_e32 v163, v74, v163
	v_add_f32_e32 v163, v75, v163
	ds_read_b64_tr_b16 v[204:205], v181 offset:0x2400
	ds_read_b64_tr_b16 v[206:207], v181 offset:0x2c00
	s_add_i32 s87, s87, 2
	s_and_b64 vcc, exec, s[62:63]
	v_mfma_f32_32x32x16_bf16 v[50:65], v[70:73], v[208:211], v[50:65]
	v_add_f32_e32 v163, v76, v163
	v_add_f32_e32 v163, v77, v163
	ds_read_b64_tr_b16 v[208:209], v181 offset:0x3400
	ds_read_b64_tr_b16 v[210:211], v181 offset:0x3c00
	s_waitcnt lgkmcnt(4)
	v_mfma_f32_32x32x16_bf16 v[34:49], v[66:69], v[82:85], v[34:49]
	v_add_f32_e32 v163, v78, v163
	v_add_f32_e32 v163, v79, v163
	ds_read_b64_tr_b16 v[82:83], v181 offset:0x2600
	ds_read_b64_tr_b16 v[84:85], v181 offset:0x2e00
	v_mfma_f32_32x32x16_bf16 v[34:49], v[70:73], v[86:89], v[34:49]
	v_add_f32_e32 v163, v80, v163
	v_add_f32_e32 v163, v81, v163
	ds_read_b64_tr_b16 v[86:87], v181 offset:0x3600
	ds_read_b64_tr_b16 v[88:89], v181 offset:0x3e00
	s_waitcnt vmcnt(0) lgkmcnt(0)
	v_mfma_f32_32x32x16_bf16 v[18:33], v[66:69], v[204:207], v[18:33]
	s_barrier
	v_mfma_f32_32x32x16_bf16 v[2:17], v[66:69], v[82:85], v[2:17]
	v_mfma_f32_32x32x16_bf16 v[18:33], v[70:73], v[208:211], v[18:33]
	v_mfma_f32_32x32x16_bf16 v[2:17], v[70:73], v[86:89], v[2:17]
	v_fma_f32 v197, v202, v93, v163
	s_cbranch_vccnz .LBB0_542

; __device__ __forceinline__ void sm_half(f32x16& p, float& m_reg, float& l_reg, float& alpha, bf16x8& paL, bf16x8& paH) {
;   float a = fmaxf(fmaxf(p[0], p[1]), p[2]), b = fmaxf(fmaxf(p[3], p[4]), p[5]);
;   a = fmaxf(fmaxf(a, p[6]), p[7]); b = fmaxf(fmaxf(b, p[8]), p[9]); a = fmaxf(fmaxf(a, p[10]), p[11]); b = fmaxf(fmaxf(b, p[12]), p[13]); a = fmaxf(fmaxf(a, p[14]), p[15]);
;   float pmax = fmaxf(a, b);
;   { auto rr = __builtin_amdgcn_permlane32_swap(__float_as_uint(pmax), __float_as_uint(pmax), false, false);
;     pmax = fmaxf(__uint_as_float(rr[0]), __uint_as_float(rr[1])); }
;   const bool keep = __all(pmax - m_reg <= THRL);
;   const float mn = keep ? m_reg : fmaxf(m_reg, pmax);
;   alpha = __builtin_amdgcn_exp2f(m_reg - mn); m_reg = mn;
; #pragma unroll
;   for (int r = 0; r < 16; ++r) p[r] = __builtin_amdgcn_exp2f(p[r] - mn);
;   float ps = 0;
; #pragma unroll
;   for (int r = 0; r < 16; ++r) ps += p[r];
;   { auto rr = __builtin_amdgcn_permlane32_swap(__float_as_uint(ps), __float_as_uint(ps), false, false);
;     ps = __uint_as_float(rr[0]) + __uint_as_float(rr[1]); }
;   l_reg = l_reg * alpha + ps;
;     ...
;   PK4(p, 0, paL); PK4(p, 8, paH);
;     ...
; }
; template <int H> __device__ __forceinline__ void qkt_half(f32x16& p, const char* Kn, const char* Kr, const bf16x8* qr, int r32, int hi) {
;   p = f32x16{};
; #pragma unroll
;   for (int d0 = 0; d0 < 8; ++d0) { const int cb = (d0 * 16 + hi * 8) * 2;
;     const bf16x8 f = *reinterpret_cast<const bf16x8*>(Kn + KSWZ(32 * H + r32, cb)); p = __builtin_amdgcn_mfma_f32_32x32x16_bf16(f, qr[d0], p, 0, 0, 0); }
; #pragma unroll
;   for (int d0 = 0; d0 < 4; ++d0) { const int cb = (d0 * 16 + hi * 8) * 2;
;     const bf16x8 f = *reinterpret_cast<const bf16x8*>(Kr + KRSWZ(32 * H + r32, cb)); p = __builtin_amdgcn_mfma_f32_32x32x16_bf16(f, qr[8 + d0], p, 0, 0, 0); }
; }
; template <int H, int D0> __device__ __forceinline__ VFrag pv_rd(int vb) {
;   VFrag f; f.l0 = tr_read<v_rd_off(D0, 2 * H, 0)>(vb); f.h0 = tr_read<v_rd_off(D0, 2 * H, 1)>(vb); f.l1 = tr_read<v_rd_off(D0, 2 * H + 1, 0)>(vb); f.h1 = tr_read<v_rd_off(D0, 2 * H + 1, 1)>(vb); return f;
; }
; __device__ __forceinline__ void pv_mma(f32x16& od, VFrag& f, bf16x8 paL, bf16x8 paH) {
;     ...
;   od = __builtin_amdgcn_mfma_f32_32x32x16_bf16(paL, PK(f.l0, f.h0), od, 0, 0, 0);
;   od = __builtin_amdgcn_mfma_f32_32x32x16_bf16(paH, PK(f.l1, f.h1), od, 0, 0, 0);
;     ...
; }
.Lcont_01:
	v_exp_f32_e32 v66, v66
	v_exp_f32_e32 v67, v67
	v_exp_f32_e32 v68, v68
	v_exp_f32_e32 v69, v69
	v_mfma_f32_32x32x16_bf16 v[2:17], v[82:85], v[214:217], v[2:17]
	v_exp_f32_e32 v70, v70
	v_exp_f32_e32 v71, v71
	v_add_f32_e32 v201, v67, v66
	v_exp_f32_e32 v72, v72
	v_add_f32_e32 v201, v68, v201
	v_exp_f32_e32 v73, v73
	v_add_f32_e32 v201, v69, v201
	v_exp_f32_e32 v74, v74
	v_add_f32_e32 v201, v70, v201
	v_exp_f32_e32 v75, v75
	v_add_f32_e32 v201, v71, v201
	v_exp_f32_e32 v76, v76
	v_add_f32_e32 v201, v72, v201
	v_exp_f32_e32 v77, v77
	v_add_f32_e32 v201, v73, v201
	v_exp_f32_e32 v78, v78
	v_exp_f32_e32 v79, v79
	v_mfma_f32_32x32x16_bf16 v[34:49], v[86:89], v[206:209], v[34:49]
	v_exp_f32_e32 v80, v80
	v_exp_f32_e32 v81, v81
	v_mfma_f32_32x32x16_bf16 v[18:33], v[86:89], v[210:213], v[18:33]
	v_cvt_pk_bf16_f32 v66, v66, v67
	v_cvt_pk_bf16_f32 v67, v68, v69
	v_mfma_f32_32x32x16_bf16 v[2:17], v[86:89], v[94:97], v[2:17]
	v_cvt_pk_bf16_f32 v68, v70, v71
	v_cvt_pk_bf16_f32 v69, v72, v73
	v_cvt_pk_bf16_f32 v70, v74, v75
	v_cvt_pk_bf16_f32 v71, v76, v77
	v_cvt_pk_bf16_f32 v72, v78, v79
	v_cvt_pk_bf16_f32 v73, v80, v81
	s_nop 0
	v_permlane32_swap_b32_e32 v66, v68
	v_permlane32_swap_b32_e32 v67, v69
	v_permlane32_swap_b32_e32 v70, v72
	v_permlane32_swap_b32_e32 v71, v73
	s_cbranch_scc1 .LBB0_531
	s_and_saveexec_b64 s[62:63], s[0:1]
	ds_write_b32 v196, v200 offset:128
	s_or_b64 exec, exec, s[62:63]
	s_waitcnt lgkmcnt(0)
	v_add_u32_e32 v86, s80, v176
	ds_read_b128 v[90:93], v86 offset:224
	ds_read_b128 v[94:97], v86 offset:192
	ds_read_b128 v[82:85], v86 offset:160
	ds_read_b128 v[86:89], v86 offset:128
	s_waitcnt lgkmcnt(0)
	v_pk_mul_f32 v[62:63], v[62:63], v[90:91]
	v_pk_mul_f32 v[58:59], v[58:59], v[94:95]
	v_pk_mul_f32 v[54:55], v[54:55], v[82:83]
	v_pk_mul_f32 v[64:65], v[64:65], v[92:93]
	v_pk_mul_f32 v[60:61], v[60:61], v[96:97]
	v_pk_mul_f32 v[56:57], v[56:57], v[84:85]
	v_pk_mul_f32 v[52:53], v[52:53], v[88:89]
	v_pk_mul_f32 v[50:51], v[50:51], v[86:87]
	v_pk_mul_f32 v[46:47], v[46:47], v[90:91]
	v_pk_mul_f32 v[42:43], v[42:43], v[94:95]
	v_pk_mul_f32 v[38:39], v[38:39], v[82:83]
	v_pk_mul_f32 v[48:49], v[48:49], v[92:93]
	v_pk_mul_f32 v[44:45], v[44:45], v[96:97]
	v_pk_mul_f32 v[40:41], v[40:41], v[84:85]
	v_pk_mul_f32 v[36:37], v[36:37], v[88:89]
	v_pk_mul_f32 v[34:35], v[34:35], v[86:87]
	v_pk_mul_f32 v[30:31], v[30:31], v[90:91]
	v_pk_mul_f32 v[26:27], v[26:27], v[94:95]
	v_pk_mul_f32 v[22:23], v[22:23], v[82:83]
	v_pk_mul_f32 v[32:33], v[32:33], v[92:93]
	v_pk_mul_f32 v[28:29], v[28:29], v[96:97]
	v_pk_mul_f32 v[24:25], v[24:25], v[84:85]
	v_pk_mul_f32 v[20:21], v[20:21], v[88:89]
	v_pk_mul_f32 v[18:19], v[18:19], v[86:87]
	v_pk_mul_f32 v[14:15], v[14:15], v[90:91]
	v_pk_mul_f32 v[10:11], v[10:11], v[94:95]
	v_pk_mul_f32 v[6:7], v[6:7], v[82:83]
	v_pk_mul_f32 v[16:17], v[16:17], v[92:93]
	v_pk_mul_f32 v[12:13], v[12:13], v[96:97]
	v_pk_mul_f32 v[8:9], v[8:9], v[84:85]
	v_pk_mul_f32 v[4:5], v[4:5], v[88:89]
	v_pk_mul_f32 v[2:3], v[2:3], v[86:87]
.LBB0_531:
	ds_read_b64_tr_b16 v[90:91], v175 offset:0x2000
	ds_read_b64_tr_b16 v[92:93], v175 offset:0x2800
	ds_read_b64_tr_b16 v[94:95], v175 offset:0x3000
	ds_read_b64_tr_b16 v[96:97], v175 offset:0x3800
	ds_read_b64_tr_b16 v[82:83], v175 offset:0x2200
	ds_read_b64_tr_b16 v[84:85], v175 offset:0x2a00
	ds_read_b64_tr_b16 v[86:87], v175 offset:0x3200
	ds_read_b64_tr_b16 v[88:89], v175 offset:0x3a00
	s_cmp_lt_u32 s87, s79
	s_waitcnt lgkmcnt(4)
	s_cselect_b64 s[64:65], -1, 0
	v_mfma_f32_32x32x16_bf16 v[50:65], v[66:69], v[90:93], v[50:65]
	v_add_f32_e32 v201, v74, v201
	v_add_f32_e32 v201, v75, v201
	ds_read_b64_tr_b16 v[90:91], v175 offset:0x2400
	ds_read_b64_tr_b16 v[92:93], v175 offset:0x2c00
	s_cmp_ge_u32 s87, s79
	s_cselect_b64 s[62:63], -1, 0
	s_and_b64 vcc, exec, s[62:63]
	v_mfma_f32_32x32x16_bf16 v[50:65], v[70:73], v[94:97], v[50:65]
	v_add_f32_e32 v201, v76, v201
	v_add_f32_e32 v201, v77, v201
	ds_read_b64_tr_b16 v[94:95], v175 offset:0x3400
	ds_read_b64_tr_b16 v[96:97], v175 offset:0x3c00
	s_waitcnt lgkmcnt(4)
	v_mfma_f32_32x32x16_bf16 v[34:49], v[66:69], v[82:85], v[34:49]
	v_add_f32_e32 v201, v78, v201
	v_add_f32_e32 v201, v79, v201
	ds_read_b64_tr_b16 v[82:83], v175 offset:0x2600
	ds_read_b64_tr_b16 v[84:85], v175 offset:0x2e00
	v_mfma_f32_32x32x16_bf16 v[34:49], v[70:73], v[86:89], v[34:49]
	v_add_f32_e32 v201, v80, v201
	v_add_f32_e32 v201, v81, v201
	ds_read_b64_tr_b16 v[86:87], v175 offset:0x3600
	ds_read_b64_tr_b16 v[88:89], v175 offset:0x3e00
	s_waitcnt vmcnt(0) lgkmcnt(0)
	v_mfma_f32_32x32x16_bf16 v[18:33], v[66:69], v[90:93], v[18:33]
	s_barrier
	v_mfma_f32_32x32x16_bf16 v[2:17], v[66:69], v[82:85], v[2:17]
	v_mfma_f32_32x32x16_bf16 v[18:33], v[70:73], v[94:97], v[18:33]
	v_mfma_f32_32x32x16_bf16 v[2:17], v[70:73], v[86:89], v[2:17]
	s_cbranch_vccnz .LBB0_533
	s_mov_b32 m0, s82
	s_nop 0
	global_load_lds_dwordx4 v152, s[18:19]
	s_mov_b32 m0, s83
	s_nop 0
	global_load_lds_dwordx4 v153, s[18:19]
	s_add_u32 s18, s18, 0x18000
	s_addc_u32 s19, s19, 0

; __device__ __forceinline__ void sm_half(f32x16& p, float& m_reg, float& l_reg, float& alpha, bf16x8& paL, bf16x8& paH) {
;     ...
;   for (int r = 0; r < 16; ++r) p[r] = __builtin_amdgcn_exp2f(p[r] - mn);
;   float ps = 0;
; #pragma unroll
;   for (int r = 0; r < 16; ++r) ps += p[r];
;   { auto rr = __builtin_amdgcn_permlane32_swap(__float_as_uint(ps), __float_as_uint(ps), false, false);
;     ps = __uint_as_float(rr[0]) + __uint_as_float(rr[1]); }
;   l_reg = l_reg * alpha + ps;
;     ...
;   PK4(p, 0, paL); PK4(p, 8, paH);
.Lcont_11:
	s_waitcnt lgkmcnt(0)
	v_mfma_f32_32x32x16_bf16 v[50:65], v[86:89], v[164:167], v[50:65]
	v_exp_f32_e32 v66, v66
	v_exp_f32_e32 v67, v67
	v_mfma_f32_32x32x16_bf16 v[34:49], v[82:85], v[168:171], v[34:49]
	v_exp_f32_e32 v68, v68
	v_exp_f32_e32 v69, v69
	v_exp_f32_e32 v70, v70
	v_exp_f32_e32 v71, v71
	v_mfma_f32_32x32x16_bf16 v[2:17], v[82:85], v[212:215], v[2:17]
	v_exp_f32_e32 v74, v74
	v_exp_f32_e32 v75, v75
	v_exp_f32_e32 v76, v76
	v_exp_f32_e32 v77, v77
	v_exp_f32_e32 v78, v78
	v_exp_f32_e32 v79, v79
	v_exp_f32_e32 v80, v80
	v_exp_f32_e32 v81, v81
	v_add_f32_e32 v163, v67, v66
	v_exp_f32_e32 v72, v72
	v_add_f32_e32 v163, v68, v163
	v_exp_f32_e32 v73, v73
	v_add_f32_e32 v163, v69, v163
	v_add_f32_e32 v163, v70, v163
	v_add_f32_e32 v163, v71, v163
	v_add_f32_e32 v163, v72, v163
	v_add_f32_e32 v163, v73, v163
	v_mfma_f32_32x32x16_bf16 v[34:49], v[86:89], v[204:207], v[34:49]
	v_mfma_f32_32x32x16_bf16 v[18:33], v[86:89], v[208:211], v[18:33]
	v_cvt_pk_bf16_f32 v66, v66, v67
	v_cvt_pk_bf16_f32 v67, v68, v69
	v_cvt_pk_bf16_f32 v68, v70, v71
	v_cvt_pk_bf16_f32 v69, v72, v73
	v_cvt_pk_bf16_f32 v70, v74, v75
	v_mfma_f32_32x32x16_bf16 v[2:17], v[86:89], v[216:219], v[2:17]
	v_cvt_pk_bf16_f32 v71, v76, v77
	v_cvt_pk_bf16_f32 v72, v78, v79
	v_cvt_pk_bf16_f32 v73, v80, v81
	s_nop 0
	v_permlane32_swap_b32_e32 v66, v68
	v_permlane32_swap_b32_e32 v67, v69
	v_permlane32_swap_b32_e32 v70, v72
	v_permlane32_swap_b32_e32 v71, v73
	s_cbranch_scc1 .LBB0_518
	s_and_saveexec_b64 s[64:65], s[0:1]
	s_cbranch_execz .LBB0_517
	ds_write_b32 v196, v93 offset:128
	s_branch .LBB0_517
